# phase 6: odd workgroups run the RWKV prompt unit first and the sample units afterwards (the others the other way round)
# baseline (speedup 1.0000x reference)
.LBB0_1289:
.LBB0_1290:
	s_cmp_lt_i32 s50, 7
	s_cselect_b64 s[0:1], -1, 0
	s_and_b64 s[24:25], s[0:1], s[4:5]
	s_andn2_b64 vcc, exec, s[24:25]
	s_cbranch_vccnz .LBB0_1378
	s_mov_b32 s95, 0
	s_bitcmp1_b32 s2, 0
	s_cbranch_scc0 .Lp6_sample_first
	s_mov_b32 s95, 1
	s_branch .LBB0_1318
.Lp6_sample_first:
	s_cmpk_gt_i32 s2, 0x7ff
	s_cbranch_scc1 .LBB0_1318
.Lp6_sample:
	s_and_b32 s52, s2, 15
	v_readfirstlane_b32 s33, v179
	v_mov_b32_e32 v77, 0
	v_and_b32_e32 v184, 63, v178
	v_lshlrev_b32_e32 v230, 1, v184
	v_lshlrev_b32_e32 v231, 2, v184
	v_and_b32_e32 v210, 15, v178
	v_lshrrev_b32_e32 v185, 3, v178
	v_and_b32_e32 v185, 0x3e, v185
	v_lshlrev_b32_e32 v233, 8, v185
	v_lshl_add_u32 v233, v210, 4, v233
	v_lshlrev_b32_e32 v159, 4, v210
	v_lshlrev_b32_e32 v208, 3, v185
	v_add_u32_e32 v208, 0x500, v208
	s_movk_i32 s0, 0x5200
	v_mul_lo_u32 v234, v210, s0
	v_lshl_add_u32 v234, v185, 1, v234
	s_mul_i32 s0, s33, 0x700
	v_add_u32_e32 v235, s0, v231
	v_and_b32_e32 v244, 1, v184
	v_lshlrev_b32_e32 v244, 2, v244
	v_lshrrev_b32_e32 v189, 1, v184
	v_lshl_add_u32 v244, v189, 4, v244
	s_add_i32 s0, s0, 0x500
	v_add_u32_e32 v244, s0, v244
	v_mov_b32_e32 v162, 0
	v_mov_b32_e32 v163, 0
	v_mov_b32_e32 v164, 0
	v_mov_b32_e32 v165, 0
	v_mov_b32_e32 v173, 0
	v_mov_b32_e32 v166, 0
	v_mov_b32_e32 v167, 0
	v_mov_b32_e32 v168, 0
	v_mov_b32_e32 v169, 0
	v_mov_b32_e32 v170, 0
	v_mov_b32_e32 v171, 0
	v_mov_b32_e32 v172, 0
	v_mov_b32_e32 v174, 0
	v_mov_b32_e32 v175, 0
	v_mov_b32_e32 v176, 0
	v_mov_b32_e32 v177, 0
	v_mov_b32_e32 v186, 0x20020
	v_mov_b32_e32 v187, 0x20080
	v_mov_b32_e32 v188, 0x200b0
	ds_read_b128 v[216:219], v186
	ds_read_b64 v[220:221], v187
	ds_read_b128 v[236:239], v188
	s_waitcnt lgkmcnt(0)
	v_readfirstlane_b32 s54, v216
	v_readfirstlane_b32 s55, v217
	v_readfirstlane_b32 s56, v218
	v_readfirstlane_b32 s57, v219
	v_readfirstlane_b32 s58, v220
	v_readfirstlane_b32 s59, v221
	v_readfirstlane_b32 s60, v236
	v_readfirstlane_b32 s61, v237
	v_readfirstlane_b32 s66, v238
	v_readfirstlane_b32 s67, v239
	s_lshl_b32 s0, s52, 8
	s_add_u32 s58, s58, s0
	s_addc_u32 s59, s59, 0
	global_load_dword v224, v231, s[58:59]
	s_add_u32 s58, s58, 0x1000
	s_addc_u32 s59, s59, 0
	global_load_dword v225, v231, s[58:59]
	s_add_u32 s58, s58, 0x1000
	s_addc_u32 s59, s59, 0
	global_load_dword v226, v231, s[58:59]
	s_add_u32 s60, s60, s0
	s_addc_u32 s61, s61, 0
	global_load_dword v227, v231, s[60:61]
	s_add_u32 s66, s66, s0
	s_addc_u32 s67, s67, 0
	global_load_dword v228, v231, s[66:67]
	s_mov_b32 s53, s2
	s_mov_b32 s99, 0
	s_lshr_b32 s1, s53, 4
	s_lshl_b32 s0, s1, 3
	s_add_i32 s0, s0, 0x4000
	s_add_i32 s66, s0, s33
	s_lshl_b32 s67, s52, 7
	s_lshl_b32 s60, s53, 14
	s_add_u32 s60, s56, s60
	s_addc_u32 s61, s57, 0
	global_load_dwordx4 v[216:219], v233, s[60:61]
	global_load_dwordx4 v[220:223], v233, s[60:61] offset:256
	s_mul_i32 s58, s66, 0x5200
	s_add_u32 s58, s58, s67
	s_add_u32 s58, s58, 0x5203000
	s_add_u32 s58, s46, s58
	s_addc_u32 s59, s47, 0
	global_load_short_d16_hi v162, v230, s[58:59] offset:-2048
	global_load_short_d16_hi v163, v230, s[58:59]
	global_load_short_d16_hi v164, v230, s[58:59] offset:2048
	s_cmp_eq_u32 s33, 0
	s_cbranch_scc1 .Lrws_shift_a
	s_sub_u32 s60, s58, 0x5200
	s_subb_u32 s61, s59, 0
	global_load_short_d16_hi v175, v230, s[60:61] offset:-2048
	global_load_short_d16_hi v176, v230, s[60:61]
	global_load_short_d16_hi v177, v230, s[60:61] offset:2048
	s_branch .Lrws_shiftdone_a

.Lrws_nopf:
	s_waitcnt lgkmcnt(0)
	s_barrier
	ds_read_b128 v[108:111], v156 offset:0
	ds_read_b128 v[112:115], v156 offset:256
	ds_read_b128 v[120:123], v156 offset:1024
	ds_read_b128 v[124:127], v157 offset:0
	ds_read_b128 v[116:119], v156 offset:768
	s_waitcnt lgkmcnt(0)
	ds_read_b128 v[128:131], v156 offset:1792
	ds_read_b128 v[132:135], v156 offset:2048
	ds_read_b128 v[140:143], v156 offset:2816
	ds_read_b128 v[144:147], v157 offset:1792
	ds_read_b128 v[136:139], v156 offset:2560
	v_pk_mul_f32 v[148:149], v[100:101], v[108:109] op_sel_hi:[1,0]
	v_pk_mul_f32 v[150:151], v[100:101], v[112:113] op_sel_hi:[1,0]
	v_pk_fma_f32 v[148:149], v[102:103], v[108:109], v[148:149] op_sel:[0,1,0]
	v_pk_fma_f32 v[150:151], v[102:103], v[112:113], v[150:151] op_sel:[0,1,0]
	v_pk_fma_f32 v[148:149], v[104:105], v[110:111], v[148:149] op_sel_hi:[1,0,1]
	v_pk_fma_f32 v[150:151], v[104:105], v[114:115], v[150:151] op_sel_hi:[1,0,1]
	v_pk_fma_f32 v[148:149], v[106:107], v[110:111], v[148:149] op_sel:[0,1,0]
	v_pk_fma_f32 v[150:151], v[106:107], v[114:115], v[150:151] op_sel:[0,1,0]
	v_pk_fma_f32 v[100:101], v[124:125], v[120:121], v[100:101] op_sel_hi:[1,0,1]
	v_add_f32_dpp v148, v148, v148 quad_perm:[1,0,3,2] row_mask:0xf bank_mask:0xf bound_ctrl:1
	v_add_f32_dpp v149, v149, v149 quad_perm:[1,0,3,2] row_mask:0xf bank_mask:0xf bound_ctrl:1
	v_add_f32_dpp v150, v150, v150 quad_perm:[1,0,3,2] row_mask:0xf bank_mask:0xf bound_ctrl:1
	v_add_f32_dpp v151, v151, v151 quad_perm:[1,0,3,2] row_mask:0xf bank_mask:0xf bound_ctrl:1
	v_pk_fma_f32 v[102:103], v[124:125], v[120:121], v[102:103] op_sel:[0,1,0]
	v_add_f32_dpp v148, v148, v148 quad_perm:[2,3,0,1] row_mask:0xf bank_mask:0xf bound_ctrl:1
	v_add_f32_dpp v149, v149, v149 quad_perm:[2,3,0,1] row_mask:0xf bank_mask:0xf bound_ctrl:1
	v_add_f32_dpp v150, v150, v150 quad_perm:[2,3,0,1] row_mask:0xf bank_mask:0xf bound_ctrl:1
	v_add_f32_dpp v151, v151, v151 quad_perm:[2,3,0,1] row_mask:0xf bank_mask:0xf bound_ctrl:1
	v_pk_fma_f32 v[104:105], v[124:125], v[122:123], v[104:105] op_sel_hi:[1,0,1]
	v_add_f32_dpp v148, v148, v148 row_half_mirror row_mask:0xf bank_mask:0xf bound_ctrl:1
	v_add_f32_dpp v149, v149, v149 row_half_mirror row_mask:0xf bank_mask:0xf bound_ctrl:1
	v_add_f32_dpp v150, v150, v150 row_half_mirror row_mask:0xf bank_mask:0xf bound_ctrl:1
	v_add_f32_dpp v151, v151, v151 row_half_mirror row_mask:0xf bank_mask:0xf bound_ctrl:1
	v_pk_fma_f32 v[106:107], v[124:125], v[122:123], v[106:107] op_sel:[0,1,0]
	v_add_f32_dpp v148, v148, v148 row_mirror row_mask:0xf bank_mask:0xf bound_ctrl:1
	v_add_f32_dpp v149, v149, v149 row_mirror row_mask:0xf bank_mask:0xf bound_ctrl:1
	v_add_f32_dpp v150, v150, v150 row_mirror row_mask:0xf bank_mask:0xf bound_ctrl:1
	v_pk_fma_f32 v[100:101], v[148:149], v[116:117], v[100:101] op_sel_hi:[1,0,1]
	v_pk_fma_f32 v[102:103], v[148:149], v[116:117], v[102:103] op_sel:[0,1,0]
	v_pk_fma_f32 v[104:105], v[148:149], v[118:119], v[104:105] op_sel_hi:[1,0,1]
	v_pk_fma_f32 v[106:107], v[148:149], v[118:119], v[106:107] op_sel:[0,1,0]
	v_add_f32_dpp v151, v151, v151 row_mirror row_mask:0xf bank_mask:0xf bound_ctrl:1
	v_pk_fma_f32 v[152:153], v[124:125], v[126:127], v[150:151] op_sel_hi:[1,0,1]
	v_cvt_pk_bf16_f32 v154, v152, v153
	s_waitcnt lgkmcnt(0)
	ds_read_b128 v[108:111], v156 offset:3584
	ds_read_b128 v[112:115], v156 offset:3840
	ds_read_b128 v[120:123], v156 offset:4608
	ds_read_b128 v[124:127], v157 offset:3584
	ds_read_b128 v[116:119], v156 offset:4352
	v_mov_b32_e32 v155, v154
	v_pk_mul_f32 v[148:149], v[100:101], v[128:129] op_sel_hi:[1,0]
	v_pk_mul_f32 v[150:151], v[100:101], v[132:133] op_sel_hi:[1,0]
	v_pk_fma_f32 v[148:149], v[102:103], v[128:129], v[148:149] op_sel:[0,1,0]
	v_pk_fma_f32 v[150:151], v[102:103], v[132:133], v[150:151] op_sel:[0,1,0]
	v_pk_fma_f32 v[148:149], v[104:105], v[130:131], v[148:149] op_sel_hi:[1,0,1]
	v_pk_fma_f32 v[150:151], v[104:105], v[134:135], v[150:151] op_sel_hi:[1,0,1]
	v_pk_fma_f32 v[148:149], v[106:107], v[130:131], v[148:149] op_sel:[0,1,0]
	v_pk_fma_f32 v[150:151], v[106:107], v[134:135], v[150:151] op_sel:[0,1,0]
	v_pk_fma_f32 v[100:101], v[144:145], v[140:141], v[100:101] op_sel_hi:[1,0,1]
	v_add_f32_dpp v148, v148, v148 quad_perm:[1,0,3,2] row_mask:0xf bank_mask:0xf bound_ctrl:1
	v_add_f32_dpp v149, v149, v149 quad_perm:[1,0,3,2] row_mask:0xf bank_mask:0xf bound_ctrl:1
	v_add_f32_dpp v150, v150, v150 quad_perm:[1,0,3,2] row_mask:0xf bank_mask:0xf bound_ctrl:1
	v_add_f32_dpp v151, v151, v151 quad_perm:[1,0,3,2] row_mask:0xf bank_mask:0xf bound_ctrl:1
	v_pk_fma_f32 v[102:103], v[144:145], v[140:141], v[102:103] op_sel:[0,1,0]
	v_add_f32_dpp v148, v148, v148 quad_perm:[2,3,0,1] row_mask:0xf bank_mask:0xf bound_ctrl:1
	v_add_f32_dpp v149, v149, v149 quad_perm:[2,3,0,1] row_mask:0xf bank_mask:0xf bound_ctrl:1
	v_add_f32_dpp v150, v150, v150 quad_perm:[2,3,0,1] row_mask:0xf bank_mask:0xf bound_ctrl:1
	v_add_f32_dpp v151, v151, v151 quad_perm:[2,3,0,1] row_mask:0xf bank_mask:0xf bound_ctrl:1
	v_pk_fma_f32 v[104:105], v[144:145], v[142:143], v[104:105] op_sel_hi:[1,0,1]
	v_add_f32_dpp v148, v148, v148 row_half_mirror row_mask:0xf bank_mask:0xf bound_ctrl:1
	v_add_f32_dpp v149, v149, v149 row_half_mirror row_mask:0xf bank_mask:0xf bound_ctrl:1
	v_add_f32_dpp v150, v150, v150 row_half_mirror row_mask:0xf bank_mask:0xf bound_ctrl:1
	v_add_f32_dpp v151, v151, v151 row_half_mirror row_mask:0xf bank_mask:0xf bound_ctrl:1
	v_pk_fma_f32 v[106:107], v[144:145], v[142:143], v[106:107] op_sel:[0,1,0]
	v_add_f32_dpp v148, v148, v148 row_mirror row_mask:0xf bank_mask:0xf bound_ctrl:1
	v_add_f32_dpp v149, v149, v149 row_mirror row_mask:0xf bank_mask:0xf bound_ctrl:1
	v_add_f32_dpp v150, v150, v150 row_mirror row_mask:0xf bank_mask:0xf bound_ctrl:1
	v_pk_fma_f32 v[100:101], v[148:149], v[136:137], v[100:101] op_sel_hi:[1,0,1]
	v_pk_fma_f32 v[102:103], v[148:149], v[136:137], v[102:103] op_sel:[0,1,0]
	v_pk_fma_f32 v[104:105], v[148:149], v[138:139], v[104:105] op_sel_hi:[1,0,1]
	v_pk_fma_f32 v[106:107], v[148:149], v[138:139], v[106:107] op_sel:[0,1,0]
	v_add_f32_dpp v151, v151, v151 row_mirror row_mask:0xf bank_mask:0xf bound_ctrl:1
	v_pk_fma_f32 v[152:153], v[144:145], v[146:147], v[150:151] op_sel_hi:[1,0,1]
	v_cvt_pk_bf16_f32 v154, v152, v153
	s_waitcnt lgkmcnt(0)
	ds_read_b128 v[128:131], v156 offset:5376
	ds_read_b128 v[132:135], v156 offset:5632
	ds_read_b128 v[140:143], v156 offset:6400
	ds_read_b128 v[144:147], v157 offset:5376
	ds_read_b128 v[136:139], v156 offset:6144
	v_mov_b32_dpp v155, v154 row_shr:1 row_mask:0xf bank_mask:0xf
	v_pk_mul_f32 v[148:149], v[100:101], v[108:109] op_sel_hi:[1,0]
	v_pk_mul_f32 v[150:151], v[100:101], v[112:113] op_sel_hi:[1,0]
	v_pk_fma_f32 v[148:149], v[102:103], v[108:109], v[148:149] op_sel:[0,1,0]
	v_pk_fma_f32 v[150:151], v[102:103], v[112:113], v[150:151] op_sel:[0,1,0]
	v_pk_fma_f32 v[148:149], v[104:105], v[110:111], v[148:149] op_sel_hi:[1,0,1]
	v_pk_fma_f32 v[150:151], v[104:105], v[114:115], v[150:151] op_sel_hi:[1,0,1]
	v_pk_fma_f32 v[148:149], v[106:107], v[110:111], v[148:149] op_sel:[0,1,0]
	v_pk_fma_f32 v[150:151], v[106:107], v[114:115], v[150:151] op_sel:[0,1,0]
	v_pk_fma_f32 v[100:101], v[124:125], v[120:121], v[100:101] op_sel_hi:[1,0,1]
	v_add_f32_dpp v148, v148, v148 quad_perm:[1,0,3,2] row_mask:0xf bank_mask:0xf bound_ctrl:1
	v_add_f32_dpp v149, v149, v149 quad_perm:[1,0,3,2] row_mask:0xf bank_mask:0xf bound_ctrl:1
	v_add_f32_dpp v150, v150, v150 quad_perm:[1,0,3,2] row_mask:0xf bank_mask:0xf bound_ctrl:1
	v_add_f32_dpp v151, v151, v151 quad_perm:[1,0,3,2] row_mask:0xf bank_mask:0xf bound_ctrl:1
	v_pk_fma_f32 v[102:103], v[124:125], v[120:121], v[102:103] op_sel:[0,1,0]
	v_add_f32_dpp v148, v148, v148 quad_perm:[2,3,0,1] row_mask:0xf bank_mask:0xf bound_ctrl:1
	v_add_f32_dpp v149, v149, v149 quad_perm:[2,3,0,1] row_mask:0xf bank_mask:0xf bound_ctrl:1
	v_add_f32_dpp v150, v150, v150 quad_perm:[2,3,0,1] row_mask:0xf bank_mask:0xf bound_ctrl:1
	v_add_f32_dpp v151, v151, v151 quad_perm:[2,3,0,1] row_mask:0xf bank_mask:0xf bound_ctrl:1
	v_pk_fma_f32 v[104:105], v[124:125], v[122:123], v[104:105] op_sel_hi:[1,0,1]
	v_add_f32_dpp v148, v148, v148 row_half_mirror row_mask:0xf bank_mask:0xf bound_ctrl:1
	v_add_f32_dpp v149, v149, v149 row_half_mirror row_mask:0xf bank_mask:0xf bound_ctrl:1
	v_add_f32_dpp v150, v150, v150 row_half_mirror row_mask:0xf bank_mask:0xf bound_ctrl:1
	v_add_f32_dpp v151, v151, v151 row_half_mirror row_mask:0xf bank_mask:0xf bound_ctrl:1
	v_pk_fma_f32 v[106:107], v[124:125], v[122:123], v[106:107] op_sel:[0,1,0]
	v_add_f32_dpp v148, v148, v148 row_mirror row_mask:0xf bank_mask:0xf bound_ctrl:1
	v_add_f32_dpp v149, v149, v149 row_mirror row_mask:0xf bank_mask:0xf bound_ctrl:1
	v_add_f32_dpp v150, v150, v150 row_mirror row_mask:0xf bank_mask:0xf bound_ctrl:1
	v_pk_fma_f32 v[100:101], v[148:149], v[116:117], v[100:101] op_sel_hi:[1,0,1]
	v_pk_fma_f32 v[102:103], v[148:149], v[116:117], v[102:103] op_sel:[0,1,0]
	v_pk_fma_f32 v[104:105], v[148:149], v[118:119], v[104:105] op_sel_hi:[1,0,1]
	v_pk_fma_f32 v[106:107], v[148:149], v[118:119], v[106:107] op_sel:[0,1,0]
	v_add_f32_dpp v151, v151, v151 row_mirror row_mask:0xf bank_mask:0xf bound_ctrl:1
	v_pk_fma_f32 v[152:153], v[124:125], v[126:127], v[150:151] op_sel_hi:[1,0,1]
	v_cvt_pk_bf16_f32 v154, v152, v153
	s_waitcnt lgkmcnt(0)
	ds_read_b128 v[108:111], v156 offset:7168
	ds_read_b128 v[112:115], v156 offset:7424
	ds_read_b128 v[120:123], v156 offset:8192
	ds_read_b128 v[124:127], v157 offset:7168
	ds_read_b128 v[116:119], v156 offset:7936
	v_mov_b32_dpp v155, v154 row_shr:2 row_mask:0xf bank_mask:0xf
	v_pk_mul_f32 v[148:149], v[100:101], v[128:129] op_sel_hi:[1,0]
	v_pk_mul_f32 v[150:151], v[100:101], v[132:133] op_sel_hi:[1,0]
	v_pk_fma_f32 v[148:149], v[102:103], v[128:129], v[148:149] op_sel:[0,1,0]
	v_pk_fma_f32 v[150:151], v[102:103], v[132:133], v[150:151] op_sel:[0,1,0]
	v_pk_fma_f32 v[148:149], v[104:105], v[130:131], v[148:149] op_sel_hi:[1,0,1]
	v_pk_fma_f32 v[150:151], v[104:105], v[134:135], v[150:151] op_sel_hi:[1,0,1]
	v_pk_fma_f32 v[148:149], v[106:107], v[130:131], v[148:149] op_sel:[0,1,0]
	v_pk_fma_f32 v[150:151], v[106:107], v[134:135], v[150:151] op_sel:[0,1,0]
	v_pk_fma_f32 v[100:101], v[144:145], v[140:141], v[100:101] op_sel_hi:[1,0,1]
	v_add_f32_dpp v148, v148, v148 quad_perm:[1,0,3,2] row_mask:0xf bank_mask:0xf bound_ctrl:1
	v_add_f32_dpp v149, v149, v149 quad_perm:[1,0,3,2] row_mask:0xf bank_mask:0xf bound_ctrl:1
	v_add_f32_dpp v150, v150, v150 quad_perm:[1,0,3,2] row_mask:0xf bank_mask:0xf bound_ctrl:1
	v_add_f32_dpp v151, v151, v151 quad_perm:[1,0,3,2] row_mask:0xf bank_mask:0xf bound_ctrl:1
	v_pk_fma_f32 v[102:103], v[144:145], v[140:141], v[102:103] op_sel:[0,1,0]
	v_add_f32_dpp v148, v148, v148 quad_perm:[2,3,0,1] row_mask:0xf bank_mask:0xf bound_ctrl:1
	v_add_f32_dpp v149, v149, v149 quad_perm:[2,3,0,1] row_mask:0xf bank_mask:0xf bound_ctrl:1
	v_add_f32_dpp v150, v150, v150 quad_perm:[2,3,0,1] row_mask:0xf bank_mask:0xf bound_ctrl:1
	v_add_f32_dpp v151, v151, v151 quad_perm:[2,3,0,1] row_mask:0xf bank_mask:0xf bound_ctrl:1
	v_pk_fma_f32 v[104:105], v[144:145], v[142:143], v[104:105] op_sel_hi:[1,0,1]
	v_add_f32_dpp v148, v148, v148 row_half_mirror row_mask:0xf bank_mask:0xf bound_ctrl:1
	v_add_f32_dpp v149, v149, v149 row_half_mirror row_mask:0xf bank_mask:0xf bound_ctrl:1
	v_add_f32_dpp v150, v150, v150 row_half_mirror row_mask:0xf bank_mask:0xf bound_ctrl:1
	v_add_f32_dpp v151, v151, v151 row_half_mirror row_mask:0xf bank_mask:0xf bound_ctrl:1
	v_pk_fma_f32 v[106:107], v[144:145], v[142:143], v[106:107] op_sel:[0,1,0]
	v_add_f32_dpp v148, v148, v148 row_mirror row_mask:0xf bank_mask:0xf bound_ctrl:1
	v_add_f32_dpp v149, v149, v149 row_mirror row_mask:0xf bank_mask:0xf bound_ctrl:1
	v_add_f32_dpp v150, v150, v150 row_mirror row_mask:0xf bank_mask:0xf bound_ctrl:1
	v_pk_fma_f32 v[100:101], v[148:149], v[136:137], v[100:101] op_sel_hi:[1,0,1]
	v_pk_fma_f32 v[102:103], v[148:149], v[136:137], v[102:103] op_sel:[0,1,0]
	v_pk_fma_f32 v[104:105], v[148:149], v[138:139], v[104:105] op_sel_hi:[1,0,1]
	v_pk_fma_f32 v[106:107], v[148:149], v[138:139], v[106:107] op_sel:[0,1,0]
	v_add_f32_dpp v151, v151, v151 row_mirror row_mask:0xf bank_mask:0xf bound_ctrl:1
	v_pk_fma_f32 v[152:153], v[144:145], v[146:147], v[150:151] op_sel_hi:[1,0,1]
	v_cvt_pk_bf16_f32 v154, v152, v153
	s_waitcnt lgkmcnt(0)
	ds_read_b128 v[128:131], v156 offset:8960
	ds_read_b128 v[132:135], v156 offset:9216
	ds_read_b128 v[140:143], v156 offset:9984
	ds_read_b128 v[144:147], v157 offset:8960
	ds_read_b128 v[136:139], v156 offset:9728
	v_mov_b32_dpp v155, v154 row_shr:3 row_mask:0xf bank_mask:0xf
	v_pk_mul_f32 v[148:149], v[100:101], v[108:109] op_sel_hi:[1,0]
	v_pk_mul_f32 v[150:151], v[100:101], v[112:113] op_sel_hi:[1,0]
	v_pk_fma_f32 v[148:149], v[102:103], v[108:109], v[148:149] op_sel:[0,1,0]
	v_pk_fma_f32 v[150:151], v[102:103], v[112:113], v[150:151] op_sel:[0,1,0]
	v_pk_fma_f32 v[148:149], v[104:105], v[110:111], v[148:149] op_sel_hi:[1,0,1]
	v_pk_fma_f32 v[150:151], v[104:105], v[114:115], v[150:151] op_sel_hi:[1,0,1]
	v_pk_fma_f32 v[148:149], v[106:107], v[110:111], v[148:149] op_sel:[0,1,0]
	v_pk_fma_f32 v[150:151], v[106:107], v[114:115], v[150:151] op_sel:[0,1,0]
	v_pk_fma_f32 v[100:101], v[124:125], v[120:121], v[100:101] op_sel_hi:[1,0,1]
	v_add_f32_dpp v148, v148, v148 quad_perm:[1,0,3,2] row_mask:0xf bank_mask:0xf bound_ctrl:1
	v_add_f32_dpp v149, v149, v149 quad_perm:[1,0,3,2] row_mask:0xf bank_mask:0xf bound_ctrl:1
	v_add_f32_dpp v150, v150, v150 quad_perm:[1,0,3,2] row_mask:0xf bank_mask:0xf bound_ctrl:1
	v_add_f32_dpp v151, v151, v151 quad_perm:[1,0,3,2] row_mask:0xf bank_mask:0xf bound_ctrl:1
	v_pk_fma_f32 v[102:103], v[124:125], v[120:121], v[102:103] op_sel:[0,1,0]
	v_add_f32_dpp v148, v148, v148 quad_perm:[2,3,0,1] row_mask:0xf bank_mask:0xf bound_ctrl:1
	v_add_f32_dpp v149, v149, v149 quad_perm:[2,3,0,1] row_mask:0xf bank_mask:0xf bound_ctrl:1
	v_add_f32_dpp v150, v150, v150 quad_perm:[2,3,0,1] row_mask:0xf bank_mask:0xf bound_ctrl:1
	v_add_f32_dpp v151, v151, v151 quad_perm:[2,3,0,1] row_mask:0xf bank_mask:0xf bound_ctrl:1
	v_pk_fma_f32 v[104:105], v[124:125], v[122:123], v[104:105] op_sel_hi:[1,0,1]
	v_add_f32_dpp v148, v148, v148 row_half_mirror row_mask:0xf bank_mask:0xf bound_ctrl:1
	v_add_f32_dpp v149, v149, v149 row_half_mirror row_mask:0xf bank_mask:0xf bound_ctrl:1
	v_add_f32_dpp v150, v150, v150 row_half_mirror row_mask:0xf bank_mask:0xf bound_ctrl:1
	v_add_f32_dpp v151, v151, v151 row_half_mirror row_mask:0xf bank_mask:0xf bound_ctrl:1
	v_pk_fma_f32 v[106:107], v[124:125], v[122:123], v[106:107] op_sel:[0,1,0]
	v_add_f32_dpp v148, v148, v148 row_mirror row_mask:0xf bank_mask:0xf bound_ctrl:1
	v_add_f32_dpp v149, v149, v149 row_mirror row_mask:0xf bank_mask:0xf bound_ctrl:1
	v_add_f32_dpp v150, v150, v150 row_mirror row_mask:0xf bank_mask:0xf bound_ctrl:1
	v_pk_fma_f32 v[100:101], v[148:149], v[116:117], v[100:101] op_sel_hi:[1,0,1]
	v_pk_fma_f32 v[102:103], v[148:149], v[116:117], v[102:103] op_sel:[0,1,0]
	v_pk_fma_f32 v[104:105], v[148:149], v[118:119], v[104:105] op_sel_hi:[1,0,1]
	v_pk_fma_f32 v[106:107], v[148:149], v[118:119], v[106:107] op_sel:[0,1,0]
	v_add_f32_dpp v151, v151, v151 row_mirror row_mask:0xf bank_mask:0xf bound_ctrl:1
	v_pk_fma_f32 v[152:153], v[124:125], v[126:127], v[150:151] op_sel_hi:[1,0,1]
	v_cvt_pk_bf16_f32 v154, v152, v153
	s_waitcnt lgkmcnt(0)
	ds_read_b128 v[108:111], v156 offset:10752
	ds_read_b128 v[112:115], v156 offset:11008
	ds_read_b128 v[120:123], v156 offset:11776
	ds_read_b128 v[124:127], v157 offset:10752
	ds_read_b128 v[116:119], v156 offset:11520
	v_mov_b32_dpp v155, v154 row_shr:4 row_mask:0xf bank_mask:0xf
	v_pk_mul_f32 v[148:149], v[100:101], v[128:129] op_sel_hi:[1,0]
	v_pk_mul_f32 v[150:151], v[100:101], v[132:133] op_sel_hi:[1,0]
	v_pk_fma_f32 v[148:149], v[102:103], v[128:129], v[148:149] op_sel:[0,1,0]
	v_pk_fma_f32 v[150:151], v[102:103], v[132:133], v[150:151] op_sel:[0,1,0]
	v_pk_fma_f32 v[148:149], v[104:105], v[130:131], v[148:149] op_sel_hi:[1,0,1]
	v_pk_fma_f32 v[150:151], v[104:105], v[134:135], v[150:151] op_sel_hi:[1,0,1]
	v_pk_fma_f32 v[148:149], v[106:107], v[130:131], v[148:149] op_sel:[0,1,0]
	v_pk_fma_f32 v[150:151], v[106:107], v[134:135], v[150:151] op_sel:[0,1,0]
	v_pk_fma_f32 v[100:101], v[144:145], v[140:141], v[100:101] op_sel_hi:[1,0,1]
	v_add_f32_dpp v148, v148, v148 quad_perm:[1,0,3,2] row_mask:0xf bank_mask:0xf bound_ctrl:1
	v_add_f32_dpp v149, v149, v149 quad_perm:[1,0,3,2] row_mask:0xf bank_mask:0xf bound_ctrl:1
	v_add_f32_dpp v150, v150, v150 quad_perm:[1,0,3,2] row_mask:0xf bank_mask:0xf bound_ctrl:1
	v_add_f32_dpp v151, v151, v151 quad_perm:[1,0,3,2] row_mask:0xf bank_mask:0xf bound_ctrl:1
	v_pk_fma_f32 v[102:103], v[144:145], v[140:141], v[102:103] op_sel:[0,1,0]
	v_add_f32_dpp v148, v148, v148 quad_perm:[2,3,0,1] row_mask:0xf bank_mask:0xf bound_ctrl:1
	v_add_f32_dpp v149, v149, v149 quad_perm:[2,3,0,1] row_mask:0xf bank_mask:0xf bound_ctrl:1
	v_add_f32_dpp v150, v150, v150 quad_perm:[2,3,0,1] row_mask:0xf bank_mask:0xf bound_ctrl:1
	v_add_f32_dpp v151, v151, v151 quad_perm:[2,3,0,1] row_mask:0xf bank_mask:0xf bound_ctrl:1
	v_pk_fma_f32 v[104:105], v[144:145], v[142:143], v[104:105] op_sel_hi:[1,0,1]
	v_add_f32_dpp v148, v148, v148 row_half_mirror row_mask:0xf bank_mask:0xf bound_ctrl:1
	v_add_f32_dpp v149, v149, v149 row_half_mirror row_mask:0xf bank_mask:0xf bound_ctrl:1
	v_add_f32_dpp v150, v150, v150 row_half_mirror row_mask:0xf bank_mask:0xf bound_ctrl:1
	v_add_f32_dpp v151, v151, v151 row_half_mirror row_mask:0xf bank_mask:0xf bound_ctrl:1
	v_pk_fma_f32 v[106:107], v[144:145], v[142:143], v[106:107] op_sel:[0,1,0]
	v_add_f32_dpp v148, v148, v148 row_mirror row_mask:0xf bank_mask:0xf bound_ctrl:1
	v_add_f32_dpp v149, v149, v149 row_mirror row_mask:0xf bank_mask:0xf bound_ctrl:1
	v_add_f32_dpp v150, v150, v150 row_mirror row_mask:0xf bank_mask:0xf bound_ctrl:1
	v_pk_fma_f32 v[100:101], v[148:149], v[136:137], v[100:101] op_sel_hi:[1,0,1]
	v_pk_fma_f32 v[102:103], v[148:149], v[136:137], v[102:103] op_sel:[0,1,0]
	v_pk_fma_f32 v[104:105], v[148:149], v[138:139], v[104:105] op_sel_hi:[1,0,1]
	v_pk_fma_f32 v[106:107], v[148:149], v[138:139], v[106:107] op_sel:[0,1,0]
	v_add_f32_dpp v151, v151, v151 row_mirror row_mask:0xf bank_mask:0xf bound_ctrl:1
	v_pk_fma_f32 v[152:153], v[144:145], v[146:147], v[150:151] op_sel_hi:[1,0,1]
	v_cvt_pk_bf16_f32 v154, v152, v153
	s_waitcnt lgkmcnt(0)
	ds_read_b128 v[128:131], v156 offset:12544
	ds_read_b128 v[132:135], v156 offset:12800
	ds_read_b128 v[140:143], v156 offset:13568
	ds_read_b128 v[144:147], v157 offset:12544
	ds_read_b128 v[136:139], v156 offset:13312
	v_mov_b32_dpp v155, v154 row_shr:5 row_mask:0xf bank_mask:0xf
	v_pk_mul_f32 v[148:149], v[100:101], v[108:109] op_sel_hi:[1,0]
	v_pk_mul_f32 v[150:151], v[100:101], v[112:113] op_sel_hi:[1,0]
	v_pk_fma_f32 v[148:149], v[102:103], v[108:109], v[148:149] op_sel:[0,1,0]
	v_pk_fma_f32 v[150:151], v[102:103], v[112:113], v[150:151] op_sel:[0,1,0]
	v_pk_fma_f32 v[148:149], v[104:105], v[110:111], v[148:149] op_sel_hi:[1,0,1]
	v_pk_fma_f32 v[150:151], v[104:105], v[114:115], v[150:151] op_sel_hi:[1,0,1]
	v_pk_fma_f32 v[148:149], v[106:107], v[110:111], v[148:149] op_sel:[0,1,0]
	v_pk_fma_f32 v[150:151], v[106:107], v[114:115], v[150:151] op_sel:[0,1,0]
	v_pk_fma_f32 v[100:101], v[124:125], v[120:121], v[100:101] op_sel_hi:[1,0,1]
	v_add_f32_dpp v148, v148, v148 quad_perm:[1,0,3,2] row_mask:0xf bank_mask:0xf bound_ctrl:1
	v_add_f32_dpp v149, v149, v149 quad_perm:[1,0,3,2] row_mask:0xf bank_mask:0xf bound_ctrl:1
	v_add_f32_dpp v150, v150, v150 quad_perm:[1,0,3,2] row_mask:0xf bank_mask:0xf bound_ctrl:1
	v_add_f32_dpp v151, v151, v151 quad_perm:[1,0,3,2] row_mask:0xf bank_mask:0xf bound_ctrl:1
	v_pk_fma_f32 v[102:103], v[124:125], v[120:121], v[102:103] op_sel:[0,1,0]
	v_add_f32_dpp v148, v148, v148 quad_perm:[2,3,0,1] row_mask:0xf bank_mask:0xf bound_ctrl:1
	v_add_f32_dpp v149, v149, v149 quad_perm:[2,3,0,1] row_mask:0xf bank_mask:0xf bound_ctrl:1
	v_add_f32_dpp v150, v150, v150 quad_perm:[2,3,0,1] row_mask:0xf bank_mask:0xf bound_ctrl:1
	v_add_f32_dpp v151, v151, v151 quad_perm:[2,3,0,1] row_mask:0xf bank_mask:0xf bound_ctrl:1
	v_pk_fma_f32 v[104:105], v[124:125], v[122:123], v[104:105] op_sel_hi:[1,0,1]
	v_add_f32_dpp v148, v148, v148 row_half_mirror row_mask:0xf bank_mask:0xf bound_ctrl:1
	v_add_f32_dpp v149, v149, v149 row_half_mirror row_mask:0xf bank_mask:0xf bound_ctrl:1
	v_add_f32_dpp v150, v150, v150 row_half_mirror row_mask:0xf bank_mask:0xf bound_ctrl:1
	v_add_f32_dpp v151, v151, v151 row_half_mirror row_mask:0xf bank_mask:0xf bound_ctrl:1
	v_pk_fma_f32 v[106:107], v[124:125], v[122:123], v[106:107] op_sel:[0,1,0]
	v_add_f32_dpp v148, v148, v148 row_mirror row_mask:0xf bank_mask:0xf bound_ctrl:1
	v_add_f32_dpp v149, v149, v149 row_mirror row_mask:0xf bank_mask:0xf bound_ctrl:1
	v_add_f32_dpp v150, v150, v150 row_mirror row_mask:0xf bank_mask:0xf bound_ctrl:1
	v_pk_fma_f32 v[100:101], v[148:149], v[116:117], v[100:101] op_sel_hi:[1,0,1]
	v_pk_fma_f32 v[102:103], v[148:149], v[116:117], v[102:103] op_sel:[0,1,0]
	v_pk_fma_f32 v[104:105], v[148:149], v[118:119], v[104:105] op_sel_hi:[1,0,1]
	v_pk_fma_f32 v[106:107], v[148:149], v[118:119], v[106:107] op_sel:[0,1,0]
	v_add_f32_dpp v151, v151, v151 row_mirror row_mask:0xf bank_mask:0xf bound_ctrl:1
	v_pk_fma_f32 v[152:153], v[124:125], v[126:127], v[150:151] op_sel_hi:[1,0,1]
	v_cvt_pk_bf16_f32 v154, v152, v153
	s_waitcnt lgkmcnt(0)
	ds_read_b128 v[204:207], v156 offset:13056
	s_nop 0
	v_mov_b32_dpp v155, v154 row_shr:6 row_mask:0xf bank_mask:0xf
	v_pk_mul_f32 v[148:149], v[100:101], v[128:129] op_sel_hi:[1,0]
	v_pk_mul_f32 v[150:151], v[100:101], v[132:133] op_sel_hi:[1,0]
	v_pk_fma_f32 v[148:149], v[102:103], v[128:129], v[148:149] op_sel:[0,1,0]
	v_pk_fma_f32 v[150:151], v[102:103], v[132:133], v[150:151] op_sel:[0,1,0]
	v_pk_fma_f32 v[148:149], v[104:105], v[130:131], v[148:149] op_sel_hi:[1,0,1]
	v_pk_fma_f32 v[150:151], v[104:105], v[134:135], v[150:151] op_sel_hi:[1,0,1]
	v_pk_fma_f32 v[148:149], v[106:107], v[130:131], v[148:149] op_sel:[0,1,0]
	v_pk_fma_f32 v[150:151], v[106:107], v[134:135], v[150:151] op_sel:[0,1,0]
	v_pk_fma_f32 v[100:101], v[144:145], v[140:141], v[100:101] op_sel_hi:[1,0,1]
	v_add_f32_dpp v148, v148, v148 quad_perm:[1,0,3,2] row_mask:0xf bank_mask:0xf bound_ctrl:1
	v_add_f32_dpp v149, v149, v149 quad_perm:[1,0,3,2] row_mask:0xf bank_mask:0xf bound_ctrl:1
	v_add_f32_dpp v150, v150, v150 quad_perm:[1,0,3,2] row_mask:0xf bank_mask:0xf bound_ctrl:1
	v_add_f32_dpp v151, v151, v151 quad_perm:[1,0,3,2] row_mask:0xf bank_mask:0xf bound_ctrl:1
	v_pk_fma_f32 v[102:103], v[144:145], v[140:141], v[102:103] op_sel:[0,1,0]
	v_add_f32_dpp v148, v148, v148 quad_perm:[2,3,0,1] row_mask:0xf bank_mask:0xf bound_ctrl:1
	v_add_f32_dpp v149, v149, v149 quad_perm:[2,3,0,1] row_mask:0xf bank_mask:0xf bound_ctrl:1
	v_add_f32_dpp v150, v150, v150 quad_perm:[2,3,0,1] row_mask:0xf bank_mask:0xf bound_ctrl:1
	v_add_f32_dpp v151, v151, v151 quad_perm:[2,3,0,1] row_mask:0xf bank_mask:0xf bound_ctrl:1
	v_pk_fma_f32 v[104:105], v[144:145], v[142:143], v[104:105] op_sel_hi:[1,0,1]
	v_add_f32_dpp v148, v148, v148 row_half_mirror row_mask:0xf bank_mask:0xf bound_ctrl:1
	v_add_f32_dpp v149, v149, v149 row_half_mirror row_mask:0xf bank_mask:0xf bound_ctrl:1
	v_add_f32_dpp v150, v150, v150 row_half_mirror row_mask:0xf bank_mask:0xf bound_ctrl:1
	v_add_f32_dpp v151, v151, v151 row_half_mirror row_mask:0xf bank_mask:0xf bound_ctrl:1
	v_pk_fma_f32 v[106:107], v[144:145], v[142:143], v[106:107] op_sel:[0,1,0]
	v_add_f32_dpp v148, v148, v148 row_mirror row_mask:0xf bank_mask:0xf bound_ctrl:1
	v_add_f32_dpp v149, v149, v149 row_mirror row_mask:0xf bank_mask:0xf bound_ctrl:1
	v_add_f32_dpp v150, v150, v150 row_mirror row_mask:0xf bank_mask:0xf bound_ctrl:1
	v_pk_fma_f32 v[100:101], v[148:149], v[136:137], v[100:101] op_sel_hi:[1,0,1]
	v_pk_fma_f32 v[102:103], v[148:149], v[136:137], v[102:103] op_sel:[0,1,0]
	v_pk_fma_f32 v[104:105], v[148:149], v[138:139], v[104:105] op_sel_hi:[1,0,1]
	v_pk_fma_f32 v[106:107], v[148:149], v[138:139], v[106:107] op_sel:[0,1,0]
	v_add_f32_dpp v151, v151, v151 row_mirror row_mask:0xf bank_mask:0xf bound_ctrl:1
	v_pk_fma_f32 v[152:153], v[144:145], v[146:147], v[150:151] op_sel_hi:[1,0,1]
	v_cvt_pk_bf16_f32 v154, v152, v153
	s_waitcnt lgkmcnt(0)
	v_pk_mul_f32 v[100:101], v[100:101], v[204:205] op_sel_hi:[1,0]
	v_pk_mul_f32 v[102:103], v[102:103], v[204:205] op_sel:[0,1]
	v_pk_mul_f32 v[104:105], v[104:105], v[206:207] op_sel_hi:[1,0]
	v_pk_mul_f32 v[106:107], v[106:107], v[206:207] op_sel:[0,1]
	v_mov_b32_dpp v155, v154 row_shr:7 row_mask:0xf bank_mask:0xf
	s_mov_b32 s0, 0xff00ff
	s_mov_b32 s1, 0xff00ff
	s_mov_b64 exec, s[0:1]
	global_store_dword v234, v155, s[100:101]
	s_mov_b64 exec, -1
	v_mov_b32_e32 v236, v100
	v_mov_b32_e32 v240, v101
	v_mov_b32_e32 v237, v102
	v_mov_b32_e32 v241, v103
	v_mov_b32_e32 v238, v104
	v_mov_b32_e32 v242, v105
	v_mov_b32_e32 v239, v106
	v_mov_b32_e32 v243, v107
	global_store_dwordx4 v233, v[236:239], s[96:97]
	global_store_dwordx4 v233, v[240:243], s[96:97] offset:256
	s_xor_b32 s99, s99, 0x3800
	s_cmpk_lt_i32 s53, 0x800
	s_cbranch_scc1 .Lrws_unit
	s_waitcnt lgkmcnt(0)
	s_barrier
	s_cmp_eq_u32 s95, 2
	s_cbranch_scc1 .LBB0_1378

.Lp6_prompt_done:
	s_cmp_eq_u32 s95, 1
	s_cbranch_scc0 .LBB0_1378
	s_mov_b32 s95, 2
	s_cmpk_gt_i32 s2, 0x7ff
	s_cbranch_scc1 .LBB0_1378
	s_branch .Lp6_sample
